# attention phase: static s_setprio 1 for waves 4-7, reset to 0 at phase exit
# speedup vs baseline: 1.0184x; 1.0184x over previous
.LBB0_2389:
	s_setprio 0
	s_waitcnt vmcnt(0)
	s_barrier
	s_mov_b64 s[6:7], exec
	v_readlane_b32 s0, v253, 13
	v_readlane_b32 s1, v253, 14
	s_and_b64 s[0:1], s[6:7], s[0:1]
	s_mov_b64 exec, s[0:1]
	s_cbranch_execz .LBB0_2474
	s_add_i32 s1, 0, 0x20000
	v_readlane_b32 s0, v253, 12
	v_mov_b32_e32 v0, s1
	s_waitcnt vmcnt(0) expcnt(0) lgkmcnt(0)
	ds_read_b32 v2, v0
	v_readlane_b32 s8, v254, 9
	s_waitcnt lgkmcnt(0)
	v_cmp_ne_u32_e32 vcc, 0, v2
	v_mov_b32_e32 v0, s8
	ds_read_b32 v0, v0
	s_cbranch_vccnz .LBB0_2438
	s_mov_b32 s14, 1
	s_branch .LBB0_2426

.LBB0_2393:
	v_readfirstlane_b32 s0, v252
	s_nop 3
	s_cmpk_lt_u32 s0, 0x100
	s_cbranch_scc1 .Lattn_prio_skip
	s_setprio 1
